# adds B near-region (table-biased) common-step fast path on top of v7
# speedup vs baseline: 1.0027x; 1.0027x over previous
; #define LAS __attribute__((address_space(3)))
; #define SCHED_FENCE() __builtin_amdgcn_sched_barrier(0)
; __device__ __forceinline__ void step_B(const bool FAR, const LAS unsigned char* cb, const LAS unsigned char* tp0, const LAS unsigned char* tp1, const bf16x8 (&qf)[4],
;                                        f32x16& oa0, f32x16& oa1, f32x16& ob0, f32x16& ob1, float& la, float& lb) {
;     bf16x8 kfA[4], vfA[2][2], kfB[4], vfB[2][2]; f32x16 tA, tB;
;     LOADK(kfA, cb); if (!FAR) LOADT(tA, tp0); LOADV(vfA, cb);
;     SCHED_FENCE();
;     f32x16 S0, S1;
;     if (FAR) { S0 = mfma32(kfA[0], qf[0], f32x16{}); S1 = mfma32(kfA[2], qf[2], f32x16{}); }
;     else { S0 = mfma32(kfA[0], qf[0], tA); S1 = mfma32(kfA[2], qf[2], tA); }
;     S0 = mfma32(kfA[1], qf[1], S0); S1 = mfma32(kfA[3], qf[3], S1);
;     kfB[0] = *(const LAS bf16x8*)(cb + 8192); kfB[1] = *(const LAS bf16x8*)(cb + 8192 + 1024); if (!FAR) LOADT(tB, tp1);
;     SCHED_FENCE();
;     bf16x8 p0, p1, r0, r1;
;     f32x16 S2; if (FAR) S2 = mfma32(kfB[0], qf[0], f32x16{}); else S2 = mfma32(kfB[0], qf[0], tB);
;     EXP4(S0, 0); EXP4(S0, 4); SCHED_FENCE();
;     S2 = mfma32(kfB[1], qf[1], S2); EXP4(S0, 8); EXP4(S0, 12); SCHED_FENCE();
;     SUM16(S0, la); pack_p(S0, p0, p1); SCHED_FENCE();
;     f32x16 tB2; kfB[2] = *(const LAS bf16x8*)(cb + 8192 + 2048); kfB[3] = *(const LAS bf16x8*)(cb + 8192 + 3072); if (!FAR) LOADT(tB2, tp1);
;     oa0 = mfma32(vfA[0][0], p0, oa0); EXP4(S1, 0); SCHED_FENCE();
;     oa1 = mfma32(vfA[1][0], p0, oa1); EXP4(S1, 4); SCHED_FENCE();
;     oa0 = mfma32(vfA[0][1], p1, oa0); EXP4(S1, 8); SCHED_FENCE();
; __device__ __forceinline__ void blk_B(int b, int hd, int chunk, const bf16_t* QK, const bf16_t* VT, bf16_t* mixed, LAS unsigned char* lds, const float* tblg, float wfar, float lam, float osc, const float* subln, int tid, int lane, int wave) {
;     ...
;         if (c0 && c1) {
;             const bool far = qb - kb1 >= 49;
;             if (!far && !scaled) { scaled = true;
; #pragma unroll
;                 for (int i = 0; i < 16; ++i) { oa0[i] *= wfar; oa1[i] *= wfar; ob0[i] *= wfar; ob1[i] *= wfar; }
;                 la *= wfar; lb *= wfar; }
;             const int d0 = qb - kb0 < 64 ? qb - kb0 : 64, d1 = qb - kb1 < 64 ? qb - kb1 : 64;
;             step_B(far, cb, tb - d0 * 128, tb - d1 * 128, qf, oa0, oa1, ob0, ob1, la, lb);
.Lattn_b_slow:
	s_cmp_lg_u32 s18, 0
	s_cbranch_scc0 .Lattn_b_slow2
	s_cmp_gt_i32 s30, 0
	s_cbranch_scc0 .Lattn_b_slow2
	v_add_u32_e32 v0, s27, v179
	s_lshl_b32 s0, s30, 7
	v_subrev_u32_e32 v219, s0, v204
	ds_read_b128 v[146:149], v0 offset:35072
	ds_read_b128 v[150:153], v0 offset:36096
	ds_read_b128 v[154:157], v0 offset:37120
	ds_read_b128 v[158:161], v0 offset:38144
	ds_read_b128 v[114:117], v219 offset:0
	ds_read_b128 v[118:121], v219 offset:16
	ds_read_b128 v[122:125], v219 offset:64
	ds_read_b128 v[126:129], v219 offset:80
	s_waitcnt lgkmcnt(0)
	v_mfma_f32_32x32x16_bf16 v[66:81], v[146:149], v[130:133], v[114:129]
	v_mfma_f32_32x32x16_bf16 v[66:81], v[150:153], v[134:137], v[66:81]
	ds_read_b128 v[162:165], v0 offset:39168
	ds_read_b128 v[166:169], v0 offset:40192
	ds_read_b128 v[208:211], v0 offset:41216
	ds_read_b128 v[212:215], v0 offset:42240
	ds_read_b128 v[146:149], v0 offset:43264
	ds_read_b128 v[150:153], v0 offset:44288
	s_nop 4
	v_mfma_f32_32x32x16_bf16 v[82:97], v[154:157], v[138:141], v[114:129]
	v_exp_f32_e32 v66, v66
	v_exp_f32_e32 v67, v67
	v_exp_f32_e32 v68, v68
	v_exp_f32_e32 v69, v69
	v_add_f32_e32 v216, v66, v67
	v_add_f32_e32 v218, v68, v69
	v_add_f32_e32 v216, v216, v218
	v_cvt_pk_bf16_f32 v98, v66, v67
	v_cvt_pk_bf16_f32 v99, v68, v69
	v_mfma_f32_32x32x16_bf16 v[82:97], v[158:161], v[142:145], v[82:97]
	ds_read_b128 v[154:157], v0 offset:45312
	ds_read_b128 v[158:161], v0 offset:46336
	ds_read_b128 v[114:117], v219 offset:128
	ds_read_b128 v[118:121], v219 offset:144
	ds_read_b128 v[122:125], v219 offset:192
	ds_read_b128 v[126:129], v219 offset:208
	v_exp_f32_e32 v70, v70
	v_exp_f32_e32 v71, v71
	v_exp_f32_e32 v72, v72
	v_exp_f32_e32 v73, v73
	v_add_f32_e32 v217, v70, v71
	v_add_f32_e32 v218, v72, v73
	v_add_f32_e32 v217, v217, v218
	v_add_f32_e32 v216, v216, v217
	v_cvt_pk_bf16_f32 v100, v70, v71
	v_cvt_pk_bf16_f32 v101, v72, v73
	v_exp_f32_e32 v74, v74
	v_exp_f32_e32 v75, v75
	v_exp_f32_e32 v76, v76
	v_exp_f32_e32 v77, v77
	v_add_f32_e32 v217, v74, v75
	v_add_f32_e32 v218, v76, v77
	v_add_f32_e32 v217, v217, v218
	v_add_f32_e32 v216, v216, v217
	v_cvt_pk_bf16_f32 v102, v74, v75
	v_cvt_pk_bf16_f32 v103, v76, v77
	v_exp_f32_e32 v78, v78
	v_exp_f32_e32 v79, v79
	v_exp_f32_e32 v80, v80
	v_exp_f32_e32 v81, v81
	v_add_f32_e32 v217, v78, v79
	v_add_f32_e32 v218, v80, v81
	v_add_f32_e32 v217, v217, v218
	v_add_f32_e32 v216, v216, v217
	v_cvt_pk_bf16_f32 v104, v78, v79
	v_cvt_pk_bf16_f32 v105, v80, v81
	v_add_f32_e32 v200, v200, v216
	s_waitcnt lgkmcnt(8)
	v_mfma_f32_32x32x16_bf16 v[2:17], v[162:165], v[98:101], v[2:17]
	v_exp_f32_e32 v82, v82
	v_exp_f32_e32 v83, v83
	v_exp_f32_e32 v84, v84
	v_exp_f32_e32 v85, v85
	v_mfma_f32_32x32x16_bf16 v[18:33], v[208:211], v[98:101], v[18:33]
	v_add_f32_e32 v216, v82, v83
	v_add_f32_e32 v218, v84, v85
	v_add_f32_e32 v216, v216, v218
	v_cvt_pk_bf16_f32 v106, v82, v83
	v_cvt_pk_bf16_f32 v107, v84, v85
	v_mfma_f32_32x32x16_bf16 v[2:17], v[166:169], v[102:105], v[2:17]
	v_exp_f32_e32 v86, v86
	v_exp_f32_e32 v87, v87
	v_exp_f32_e32 v88, v88
	v_exp_f32_e32 v89, v89
	v_mfma_f32_32x32x16_bf16 v[18:33], v[212:215], v[102:105], v[18:33]
	s_waitcnt lgkmcnt(0)
; #define LAS __attribute__((address_space(3)))
; __device__ __forceinline__ f32x16 mfma32(bf16x8 a, bf16x8 b, f32x16 c) { return __builtin_amdgcn_mfma_f32_32x32x16_bf16(a, b, c, 0, 0, 0); }
; #define LOADV(vf_, cb_) do { _Pragma("unroll") for (int d_ = 0; d_ < 2; ++d_) _Pragma("unroll") for (int s_ = 0; s_ < 2; ++s_) vf_[d_][s_] = *(const LAS bf16x8*)((cb_) + 4096 + (d_ * 2 + s_) * 1024); } while (0)
; #define SCHED_FENCE() __builtin_amdgcn_sched_barrier(0)
; #define EXP4(S_, b_) do { S_[b_] = ex2(S_[b_]); S_[(b_) + 1] = ex2(S_[(b_) + 1]); S_[(b_) + 2] = ex2(S_[(b_) + 2]); S_[(b_) + 3] = ex2(S_[(b_) + 3]); } while (0)
; __device__ __forceinline__ void step_B(const bool FAR, const LAS unsigned char* cb, const LAS unsigned char* tp0, const LAS unsigned char* tp1, const bf16x8 (&qf)[4],
;                                        f32x16& oa0, f32x16& oa1, f32x16& ob0, f32x16& ob1, float& la, float& lb) {
;     ...
;     f32x16 tB2; kfB[2] = *(const LAS bf16x8*)(cb + 8192 + 2048); kfB[3] = *(const LAS bf16x8*)(cb + 8192 + 3072); if (!FAR) LOADT(tB2, tp1);
;     oa0 = mfma32(vfA[0][0], p0, oa0); EXP4(S1, 0); SCHED_FENCE();
;     oa1 = mfma32(vfA[1][0], p0, oa1); EXP4(S1, 4); SCHED_FENCE();
;     oa0 = mfma32(vfA[0][1], p1, oa0); EXP4(S1, 8); SCHED_FENCE();
;     oa1 = mfma32(vfA[1][1], p1, oa1); EXP4(S1, 12); SCHED_FENCE();
;     f32x16 S3; if (FAR) S3 = mfma32(kfB[2], qf[2], f32x16{}); else S3 = mfma32(kfB[2], qf[2], tB2);
;     SUM16(S1, lb); SCHED_FENCE();
;     S3 = mfma32(kfB[3], qf[3], S3); pack_p(S1, r0, r1); SCHED_FENCE();
;     LOADV(vfB, cb + 8192);
;     ob0 = mfma32(vfA[0][0], r0, ob0); EXP4(S2, 0); SCHED_FENCE();
;     ob1 = mfma32(vfA[1][0], r0, ob1); EXP4(S2, 4); SCHED_FENCE();
;     ob0 = mfma32(vfA[0][1], r1, ob0); EXP4(S2, 8); SCHED_FENCE();
;     ob1 = mfma32(vfA[1][1], r1, ob1); EXP4(S2, 12); SCHED_FENCE();
;     SUM16(S2, la); pack_p(S2, p0, p1); SCHED_FENCE();
;     oa0 = mfma32(vfB[0][0], p0, oa0); EXP4(S3, 0); SCHED_FENCE();
;     oa1 = mfma32(vfB[1][0], p0, oa1); EXP4(S3, 4); SCHED_FENCE();
;     oa0 = mfma32(vfB[0][1], p1, oa0); EXP4(S3, 8); SCHED_FENCE();
;     oa1 = mfma32(vfB[1][1], p1, oa1); EXP4(S3, 12); SCHED_FENCE();
;     SUM16(S3, lb); pack_p(S3, r0, r1); SCHED_FENCE();
;     ob0 = mfma32(vfB[0][0], r0, ob0); ob1 = mfma32(vfB[1][0], r0, ob1); ob0 = mfma32(vfB[0][1], r1, ob0); ob1 = mfma32(vfB[1][1], r1, ob1);
; }
	v_add_f32_e32 v217, v86, v87
	v_add_f32_e32 v218, v88, v89
	v_add_f32_e32 v217, v217, v218
	v_add_f32_e32 v216, v216, v217
	v_cvt_pk_bf16_f32 v108, v86, v87
	v_cvt_pk_bf16_f32 v109, v88, v89
	v_mfma_f32_32x32x16_bf16 v[66:81], v[146:149], v[130:133], v[114:129]
	v_exp_f32_e32 v90, v90
	v_exp_f32_e32 v91, v91
	v_exp_f32_e32 v92, v92
	v_exp_f32_e32 v93, v93
	v_mfma_f32_32x32x16_bf16 v[66:81], v[150:153], v[134:137], v[66:81]
	v_add_f32_e32 v217, v90, v91
	v_add_f32_e32 v218, v92, v93
	v_add_f32_e32 v217, v217, v218
	v_add_f32_e32 v216, v216, v217
	v_cvt_pk_bf16_f32 v110, v90, v91
	v_cvt_pk_bf16_f32 v111, v92, v93
	v_exp_f32_e32 v94, v94
	v_exp_f32_e32 v95, v95
	v_exp_f32_e32 v96, v96
	v_exp_f32_e32 v97, v97
	v_add_f32_e32 v217, v94, v95
	v_add_f32_e32 v218, v96, v97
	v_add_f32_e32 v217, v217, v218
	v_add_f32_e32 v216, v216, v217
	v_cvt_pk_bf16_f32 v112, v94, v95
	v_cvt_pk_bf16_f32 v113, v96, v97
	v_add_f32_e32 v201, v201, v216
	v_mfma_f32_32x32x16_bf16 v[50:65], v[162:165], v[106:109], v[50:65]
	v_exp_f32_e32 v66, v66
	v_exp_f32_e32 v67, v67
	v_exp_f32_e32 v68, v68
	v_exp_f32_e32 v69, v69
	v_mfma_f32_32x32x16_bf16 v[34:49], v[208:211], v[106:109], v[34:49]
	v_add_f32_e32 v216, v66, v67
	v_add_f32_e32 v218, v68, v69
	v_add_f32_e32 v216, v216, v218
	v_cvt_pk_bf16_f32 v98, v66, v67
	v_cvt_pk_bf16_f32 v99, v68, v69
	v_mfma_f32_32x32x16_bf16 v[50:65], v[166:169], v[110:113], v[50:65]
	v_exp_f32_e32 v70, v70
	v_exp_f32_e32 v71, v71
	v_exp_f32_e32 v72, v72
	v_exp_f32_e32 v73, v73
	v_mfma_f32_32x32x16_bf16 v[34:49], v[212:215], v[110:113], v[34:49]
	ds_read_b128 v[162:165], v0 offset:47360
	ds_read_b128 v[166:169], v0 offset:48384
	ds_read_b128 v[208:211], v0 offset:49408
	ds_read_b128 v[212:215], v0 offset:50432
	v_add_f32_e32 v217, v70, v71
	v_add_f32_e32 v218, v72, v73
	v_add_f32_e32 v217, v217, v218
	v_add_f32_e32 v216, v216, v217
	v_cvt_pk_bf16_f32 v100, v70, v71
	v_cvt_pk_bf16_f32 v101, v72, v73
	v_mfma_f32_32x32x16_bf16 v[82:97], v[154:157], v[138:141], v[114:129]
	v_exp_f32_e32 v74, v74
	v_exp_f32_e32 v75, v75
	v_exp_f32_e32 v76, v76
	v_exp_f32_e32 v77, v77
	v_mfma_f32_32x32x16_bf16 v[82:97], v[158:161], v[142:145], v[82:97]
	v_add_f32_e32 v217, v74, v75
	v_add_f32_e32 v218, v76, v77
	v_add_f32_e32 v217, v217, v218
	v_add_f32_e32 v216, v216, v217
	v_cvt_pk_bf16_f32 v102, v74, v75
	v_cvt_pk_bf16_f32 v103, v76, v77
	v_exp_f32_e32 v78, v78
	v_exp_f32_e32 v79, v79
	v_exp_f32_e32 v80, v80
	v_exp_f32_e32 v81, v81
	v_add_f32_e32 v217, v78, v79
	v_add_f32_e32 v218, v80, v81
	v_add_f32_e32 v217, v217, v218
	v_add_f32_e32 v216, v216, v217
	v_cvt_pk_bf16_f32 v104, v78, v79
	v_cvt_pk_bf16_f32 v105, v80, v81
	v_add_f32_e32 v200, v200, v216
	s_waitcnt lgkmcnt(0)
	v_mfma_f32_32x32x16_bf16 v[2:17], v[162:165], v[98:101], v[2:17]
	v_exp_f32_e32 v82, v82
	v_exp_f32_e32 v83, v83
	v_exp_f32_e32 v84, v84
	v_exp_f32_e32 v85, v85
	v_add_f32_e32 v216, v82, v83
	v_add_f32_e32 v218, v84, v85
	v_add_f32_e32 v216, v216, v218
	v_cvt_pk_bf16_f32 v106, v82, v83
	v_cvt_pk_bf16_f32 v107, v84, v85
	v_mfma_f32_32x32x16_bf16 v[18:33], v[208:211], v[98:101], v[18:33]
	v_exp_f32_e32 v86, v86
	v_exp_f32_e32 v87, v87
	v_exp_f32_e32 v88, v88
	v_exp_f32_e32 v89, v89
	v_add_f32_e32 v217, v86, v87
	v_add_f32_e32 v218, v88, v89
	v_add_f32_e32 v217, v217, v218
	v_add_f32_e32 v216, v216, v217
	v_cvt_pk_bf16_f32 v108, v86, v87
	v_cvt_pk_bf16_f32 v109, v88, v89
	v_mfma_f32_32x32x16_bf16 v[2:17], v[166:169], v[102:105], v[2:17]
	v_exp_f32_e32 v90, v90
	v_exp_f32_e32 v91, v91
	v_exp_f32_e32 v92, v92
	v_exp_f32_e32 v93, v93
	v_add_f32_e32 v217, v90, v91
	v_add_f32_e32 v218, v92, v93
	v_add_f32_e32 v217, v217, v218
	v_add_f32_e32 v216, v216, v217
	v_cvt_pk_bf16_f32 v110, v90, v91
	v_cvt_pk_bf16_f32 v111, v92, v93
	v_mfma_f32_32x32x16_bf16 v[18:33], v[212:215], v[102:105], v[18:33]
	v_exp_f32_e32 v94, v94
	v_exp_f32_e32 v95, v95
	v_exp_f32_e32 v96, v96
	v_exp_f32_e32 v97, v97
	v_add_f32_e32 v217, v94, v95
	v_add_f32_e32 v218, v96, v97
	v_add_f32_e32 v217, v217, v218
	v_add_f32_e32 v216, v216, v217
	v_cvt_pk_bf16_f32 v112, v94, v95
	v_cvt_pk_bf16_f32 v113, v96, v97
	v_add_f32_e32 v201, v201, v216
	v_mfma_f32_32x32x16_bf16 v[50:65], v[162:165], v[106:109], v[50:65]
	v_mfma_f32_32x32x16_bf16 v[34:49], v[208:211], v[106:109], v[34:49]
	v_mfma_f32_32x32x16_bf16 v[50:65], v[166:169], v[110:113], v[50:65]
	v_mfma_f32_32x32x16_bf16 v[34:49], v[212:215], v[110:113], v[34:49]
	s_branch .LBB0_355
